# compress loop: back-edge path gets its own MFMA block with wait counts that leave the next half-step loads in flight (no vmcnt(0) drain)
# baseline (speedup 1.0000x reference)
; template <bool SAMPLE>
; __device__ __forceinline__ void compress_unit(Frame& F, int l, int unit) {
;     ...
;     CMP_LOAD(0, w * 8);
; #pragma unroll 1
;     for (int li = 0; li < 8; ++li) { const int lpos = w * 8 + li;
;         CMP_LOAD(1, lpos); __builtin_amdgcn_sched_barrier(0);
;         CMP_MMA(0); __builtin_amdgcn_sched_barrier(0);
;         if (li < 7) CMP_LOAD(0, lpos + 1);
;         __builtin_amdgcn_sched_barrier(0);
;         CMP_MMA(1); __builtin_amdgcn_sched_barrier(0);
;     }
.LBB0_577:
	s_mov_b32 s22, 0x7e000
	v_add_co_u32_e32 v136, vcc, s22, v224
	s_mov_b32 s22, 0x7f000
	s_nop 0
	v_addc_co_u32_e32 v137, vcc, 0, v225, vcc
	v_add_co_u32_e32 v144, vcc, s22, v224
	v_lshl_add_u64 v[228:229], v[220:221], 0, s[66:67]
	s_nop 0
	v_addc_co_u32_e32 v145, vcc, 0, v225, vcc
	v_lshl_add_u64 v[226:227], v[222:223], 0, s[66:67]
	global_load_dwordx4 v[188:191], v[228:229], off offset:1040
	global_load_dwordx4 v[192:195], v[228:229], off offset:1024
	global_load_dwordx4 v[176:179], v[226:227], off offset:1040
	global_load_dwordx4 v[184:187], v[226:227], off offset:1024
	global_load_dwordx4 v[156:159], v[136:137], off offset:2048
	global_load_dwordx4 v[132:135], v[136:137], off offset:64
	global_load_dwordx4 v[164:167], v[144:145], off offset:-4096
	s_nop 0
	global_load_dwordx4 v[136:139], v[136:137], off offset:2112
	s_nop 0
	global_load_dwordx4 v[168:171], v[144:145], off
	global_load_dwordx4 v[140:143], v[144:145], off offset:64
	global_load_dwordx4 v[172:175], v[144:145], off offset:2048
	s_nop 0
	global_load_dwordx4 v[144:147], v[144:145], off offset:2112
	s_nop 0
	global_load_dwordx4 v[160:163], v[228:229], off offset:1168
	global_load_dwordx4 v[180:183], v[228:229], off offset:1152
	global_load_dwordx4 v[148:151], v[226:227], off offset:1168
	global_load_dwordx4 v[152:155], v[226:227], off offset:1152
	s_waitcnt vmcnt(22)
	v_cvt_pk_bf16_f32 v246, v18, v19
	v_cvt_pk_bf16_f32 v247, v20, v21
	v_cvt_pk_bf16_f32 v248, v14, v15
	v_cvt_pk_bf16_f32 v249, v16, v17
	s_nop 1
	v_mfma_f32_16x16x32_bf16 v[34:37], v[2:5], v[246:249], v[34:37]
	v_mfma_f32_16x16x32_bf16 v[50:53], v[26:29], v[246:249], v[50:53]
	v_mfma_f32_16x16x32_bf16 v[58:61], v[6:9], v[246:249], v[58:61]
	v_mfma_f32_16x16x32_bf16 v[62:65], v[10:13], v[246:249], v[62:65]
	s_waitcnt vmcnt(19)
	v_cvt_pk_bf16_f32 v246, v82, v83
	v_cvt_pk_bf16_f32 v247, v84, v85
	v_cvt_pk_bf16_f32 v248, v46, v47
	v_cvt_pk_bf16_f32 v249, v48, v49
	s_nop 1
	v_mfma_f32_16x16x32_bf16 v[66:69], v[2:5], v[246:249], v[66:69]
	v_mfma_f32_16x16x32_bf16 v[70:73], v[26:29], v[246:249], v[70:73]
	v_mfma_f32_16x16x32_bf16 v[74:77], v[6:9], v[246:249], v[74:77]
	v_mfma_f32_16x16x32_bf16 v[78:81], v[10:13], v[246:249], v[78:81]
	s_waitcnt vmcnt(17)
	v_cvt_pk_bf16_f32 v246, v54, v55
	v_cvt_pk_bf16_f32 v247, v56, v57
	v_cvt_pk_bf16_f32 v248, v90, v91
	v_cvt_pk_bf16_f32 v249, v92, v93
	s_nop 1
	v_mfma_f32_16x16x32_bf16 v[34:37], v[22:25], v[246:249], v[34:37]
	v_mfma_f32_16x16x32_bf16 v[50:53], v[30:33], v[246:249], v[50:53]
	v_mfma_f32_16x16x32_bf16 v[58:61], v[38:41], v[246:249], v[58:61]
	v_mfma_f32_16x16x32_bf16 v[62:65], v[42:45], v[246:249], v[62:65]
	s_waitcnt vmcnt(16)
	v_cvt_pk_bf16_f32 v246, v120, v121
	v_cvt_pk_bf16_f32 v247, v122, v123
	v_cvt_pk_bf16_f32 v248, v128, v129
	v_cvt_pk_bf16_f32 v249, v130, v131
	s_nop 1
	v_mfma_f32_16x16x32_bf16 v[66:69], v[22:25], v[246:249], v[66:69]
	v_mfma_f32_16x16x32_bf16 v[70:73], v[30:33], v[246:249], v[70:73]
	v_mfma_f32_16x16x32_bf16 v[74:77], v[38:41], v[246:249], v[74:77]
	v_mfma_f32_16x16x32_bf16 v[78:81], v[42:45], v[246:249], v[78:81]
	s_cmpk_eq_i32 s66, 0x7000
	s_cbranch_scc1 .LBB0_576
	v_add_co_u32_e32 v42, vcc, 0x1000, v224
	v_lshl_add_u64 v[2:3], v[228:229], 0, s[96:97]
	s_nop 0
	v_addc_co_u32_e32 v43, vcc, 0, v225, vcc
	v_add_co_u32_e32 v54, vcc, 0x1000, v228
	v_lshl_add_u64 v[46:47], v[226:227], 0, s[96:97]
	s_nop 0
	v_addc_co_u32_e32 v55, vcc, 0, v229, vcc
	global_load_dwordx4 v[18:21], v[54:55], off
	global_load_dwordx4 v[14:17], v[2:3], off offset:16
	s_nop 0
	global_load_dwordx4 v[2:5], v[224:225], off
	global_load_dwordx4 v[22:25], v[224:225], off offset:64
	global_load_dwordx4 v[26:29], v[224:225], off offset:2048
	global_load_dwordx4 v[30:33], v[224:225], off offset:2112
	global_load_dwordx4 v[6:9], v[42:43], off
	global_load_dwordx4 v[38:41], v[42:43], off offset:64
	global_load_dwordx4 v[10:13], v[42:43], off offset:2048
	s_nop 0
	global_load_dwordx4 v[42:45], v[42:43], off offset:2112
	v_add_co_u32_e32 v90, vcc, 0x1000, v226
	v_lshl_add_u64 v[92:93], v[228:229], 0, s[6:7]
	s_nop 0
	v_addc_co_u32_e32 v91, vcc, 0, v227, vcc
	v_lshl_add_u64 v[128:129], v[226:227], 0, s[6:7]
	global_load_dwordx4 v[46:49], v[46:47], off offset:16
	s_nop 0
	global_load_dwordx4 v[54:57], v[54:55], off offset:128
	s_nop 0
	global_load_dwordx4 v[82:85], v[90:91], off
	global_load_dwordx4 v[120:123], v[90:91], off offset:128
	s_nop 0
	global_load_dwordx4 v[90:93], v[92:93], off offset:16
	s_nop 0
	global_load_dwordx4 v[128:131], v[128:129], off offset:16
	s_waitcnt vmcnt(30)
	v_cvt_pk_bf16_f32 v192, v192, v193
	v_cvt_pk_bf16_f32 v193, v194, v195
	v_cvt_pk_bf16_f32 v194, v188, v189
	v_cvt_pk_bf16_f32 v195, v190, v191
	s_waitcnt vmcnt(28)
	v_cvt_pk_bf16_f32 v184, v184, v185
	v_cvt_pk_bf16_f32 v185, v186, v187
	v_cvt_pk_bf16_f32 v186, v176, v177
	v_cvt_pk_bf16_f32 v187, v178, v179
	s_waitcnt vmcnt(25)
	v_mfma_f32_16x16x32_bf16 v[86:89], v[164:167], v[192:195], v[86:89]
	s_waitcnt vmcnt(16)
	v_cvt_pk_bf16_f32 v152, v152, v153
	v_cvt_pk_bf16_f32 v153, v154, v155
	v_cvt_pk_bf16_f32 v154, v148, v149
	v_mfma_f32_16x16x32_bf16 v[94:97], v[156:159], v[192:195], v[94:97]
	v_cvt_pk_bf16_f32 v155, v150, v151
	v_mfma_f32_16x16x32_bf16 v[100:103], v[168:171], v[192:195], v[100:103]
	v_mfma_f32_16x16x32_bf16 v[104:107], v[172:175], v[192:195], v[104:107]
	v_mfma_f32_16x16x32_bf16 v[108:111], v[164:167], v[184:187], v[108:111]
	v_mfma_f32_16x16x32_bf16 v[112:115], v[156:159], v[184:187], v[112:115]
	v_cvt_pk_bf16_f32 v156, v180, v181
	v_cvt_pk_bf16_f32 v157, v182, v183
	v_cvt_pk_bf16_f32 v158, v160, v161
	v_mfma_f32_16x16x32_bf16 v[116:119], v[168:171], v[184:187], v[116:119]
	v_cvt_pk_bf16_f32 v159, v162, v163
	v_mfma_f32_16x16x32_bf16 v[124:127], v[172:175], v[184:187], v[124:127]
	s_nop 0
	v_mfma_f32_16x16x32_bf16 v[86:89], v[132:135], v[156:159], v[86:89]
	v_mfma_f32_16x16x32_bf16 v[94:97], v[136:139], v[156:159], v[94:97]
	v_mfma_f32_16x16x32_bf16 v[100:103], v[140:143], v[156:159], v[100:103]
	v_mfma_f32_16x16x32_bf16 v[104:107], v[144:147], v[156:159], v[104:107]
	v_mfma_f32_16x16x32_bf16 v[108:111], v[132:135], v[152:155], v[108:111]
	v_mfma_f32_16x16x32_bf16 v[112:115], v[136:139], v[152:155], v[112:115]
	v_mfma_f32_16x16x32_bf16 v[116:119], v[140:143], v[152:155], v[116:119]
	v_mfma_f32_16x16x32_bf16 v[124:127], v[144:147], v[152:155], v[124:127]
	s_add_u32 s66, s66, 0x1000
	s_addc_u32 s67, s67, 0
	s_cmpk_eq_u32 s66, 0x8000
	v_lshl_add_u64 v[224:225], v[224:225], 0, s[94:95]
	s_cbranch_scc1 .LBB0_579
	s_branch .LBB0_577
